# post1 phase: prefetch (3 dummy dwordx4 per lane) of the wave's next row at the top of each row iteration
# baseline (speedup 1.0000x reference)
; DEV unsigned pack2(float a, float b) { f32x2 v = {a, b}; return __builtin_bit_cast(unsigned, __builtin_convertvector(v, bf2_t)); }
; DEV float bflo(unsigned u) { return __uint_as_float(u << 16); }
; DEV float bfhi(unsigned u) { return __uint_as_float(u & 0xffff0000u); }
; DEV void phase_post1(const Params& p) {
;     ...
;   for (int row = blockIdx.x * 4 + wave; row < MT; row += gridDim.x * 4) {
;     const bf16_t* pr = P0 + (size_t)row * 1536;
;     {
;       uint2 u = *(const uint2*)(pr + lane * 4);
;       float a0 = bflo(u.x), a1 = bfhi(u.x), a2 = bflo(u.y), a3 = bfhi(u.y);
;       float ss = wave_sum(a0 * a0 + a1 * a1 + a2 * a2 + a3 * a3);
;       float rinv = rsqrtf(ss * (1.f / 256.f) + 1e-6f);
;       float4 g4 = ((const float4*)qg)[lane];
;       uint2 r; r.x = pack2(a0 * rinv * g4.x, a1 * rinv * g4.y); r.y = pack2(a2 * rinv * g4.z, a3 * rinv * g4.w);
;       *(uint2*)(QN + (size_t)row * 256 + lane * 4) = r;
;     }
;     {
;       unsigned u = *(const unsigned*)(pr + 256 + lane * 2);
;       float a0 = bflo(u), a1 = bfhi(u);
;       float ss = wave_sum(a0 * a0 + a1 * a1);
;       float rinv = rsqrtf(ss * (1.f / 128.f) + 1e-6f);
;       float2 g2 = ((const float2*)kvg)[lane];
;       *(unsigned*)(KVN + (size_t)row * 128 + lane * 2) = pack2(a0 * rinv * g2.x, a1 * rinv * g2.y);
;     }
.LBB0_1026:
	v_mov_b64_e32 v[2:3], s[2:3]
	s_movk_i32 s12, 0xc00
	v_mad_i64_i32 v[2:3], s[12:13], v10, s12, v[2:3]
	s_mul_i32 s16, s55, 0xc00
	s_mov_b32 s17, 0
	v_lshl_add_u64 v[40:41], v[2:3], 0, s[16:17]
	v_mov_b32_e32 v42, v26
	v_mov_b32_e32 v43, v1
	v_lshl_add_u64 v[40:41], v[40:41], 0, v[42:43]
	global_load_dwordx4 v[44:47], v[40:41], off
	global_load_dwordx4 v[48:51], v[40:41], off offset:1024
	global_load_dwordx4 v[52:55], v[40:41], off offset:2048
	v_lshl_add_u64 v[4:5], v[2:3], 0, v[0:1]
	global_load_dwordx2 v[4:5], v[4:5], off
	s_mov_b32 s12, 0x800000
	v_ashrrev_i32_e32 v11, 31, v10
	s_waitcnt vmcnt(0)
	v_lshlrev_b32_e32 v8, 16, v4
	v_and_b32_e32 v9, 0xffff0000, v4
	v_lshlrev_b32_e32 v28, 16, v5
	v_and_b32_e32 v29, 0xffff0000, v5
	global_load_dwordx4 v[4:7], v[14:15], off
	v_pk_mul_f32 v[38:39], v[8:9], v[8:9]
	v_pk_mul_f32 v[36:37], v[28:29], v[28:29]
	v_add_f32_e32 v13, v38, v39
	v_add_f32_e32 v13, v13, v36
	v_add_f32_e32 v13, v37, v13
	ds_bpermute_b32 v25, v30, v13
	s_waitcnt lgkmcnt(0)
	v_add_f32_e32 v13, v13, v25
	ds_bpermute_b32 v25, v31, v13
	s_waitcnt lgkmcnt(0)
	v_add_f32_e32 v13, v13, v25
	ds_bpermute_b32 v25, v32, v13
	s_waitcnt lgkmcnt(0)
	v_add_f32_e32 v13, v13, v25
	ds_bpermute_b32 v25, v33, v13
	s_waitcnt lgkmcnt(0)
	v_add_f32_e32 v13, v13, v25
	ds_bpermute_b32 v25, v34, v13
	s_waitcnt lgkmcnt(0)
	v_add_f32_e32 v13, v13, v25
	ds_bpermute_b32 v25, v35, v13
	s_waitcnt lgkmcnt(0)
	v_add_f32_e32 v13, v13, v25
	v_fmamk_f32 v13, v13, 0x3b800000, v211
	v_cmp_gt_f32_e32 vcc, s12, v13
	v_mul_f32_e32 v25, 0x4b800000, v13
	s_nop 0
	v_cndmask_b32_e32 v13, v13, v25, vcc
	v_rsq_f32_e32 v13, v13
	s_nop 0
	v_mul_f32_e32 v25, 0x45800000, v13
	v_cndmask_b32_e32 v36, v13, v25, vcc
	v_pk_mul_f32 v[8:9], v[36:37], v[8:9] op_sel_hi:[0,1]
	v_mov_b32_e32 v25, v1
	s_waitcnt vmcnt(0)
	v_pk_mul_f32 v[4:5], v[4:5], v[8:9]
	v_pk_mul_f32 v[8:9], v[36:37], v[28:29] op_sel_hi:[0,1]
	v_pk_mul_f32 v[6:7], v[6:7], v[8:9]
	v_cvt_pk_bf16_f32 v4, v4, v5
	v_cvt_pk_bf16_f32 v5, v6, v7
	v_lshlrev_b64 v[6:7], 9, v[10:11]
	v_lshl_add_u64 v[6:7], v[16:17], 0, v[6:7]
	global_store_dwordx2 v[6:7], v[4:5], off
	v_lshl_add_u64 v[4:5], v[2:3], 0, v[24:25]
	global_load_dword v7, v[4:5], off offset:512
	global_load_dwordx2 v[28:29], v[18:19], off
	s_waitcnt vmcnt(1)
	v_lshlrev_b32_e32 v6, 16, v7
	v_and_b32_e32 v7, 0xffff0000, v7
	v_pk_mul_f32 v[8:9], v[6:7], v[6:7]
	s_nop 0
	v_add_f32_e32 v8, v8, v9
	ds_bpermute_b32 v9, v30, v8
	s_waitcnt lgkmcnt(0)
	v_add_f32_e32 v8, v8, v9
	ds_bpermute_b32 v9, v31, v8
	s_waitcnt lgkmcnt(0)
	v_add_f32_e32 v8, v8, v9
	ds_bpermute_b32 v9, v32, v8
	s_waitcnt lgkmcnt(0)
	v_add_f32_e32 v8, v8, v9
	ds_bpermute_b32 v9, v33, v8
	s_waitcnt lgkmcnt(0)
	v_add_f32_e32 v8, v8, v9
	ds_bpermute_b32 v9, v34, v8
	s_waitcnt lgkmcnt(0)
	v_add_f32_e32 v8, v8, v9
	ds_bpermute_b32 v9, v35, v8
	s_waitcnt lgkmcnt(0)
	v_add_f32_e32 v8, v8, v9
	v_fmamk_f32 v8, v8, 0x3c000000, v211
	v_cmp_gt_f32_e32 vcc, s12, v8
	v_mul_f32_e32 v9, 0x4b800000, v8
	s_nop 0
	v_cndmask_b32_e32 v8, v8, v9, vcc
	v_rsq_f32_e32 v8, v8
	s_nop 0
	v_mul_f32_e32 v9, 0x45800000, v8
	v_cndmask_b32_e32 v8, v8, v9, vcc
	v_pk_mul_f32 v[6:7], v[8:9], v[6:7] op_sel_hi:[0,1]
	s_waitcnt vmcnt(0)
	v_pk_mul_f32 v[6:7], v[28:29], v[6:7]
	s_nop 0
	v_cvt_pk_bf16_f32 v8, v6, v7
	v_lshlrev_b64 v[6:7], 8, v[10:11]
	v_lshl_add_u64 v[6:7], v[20:21], 0, v[6:7]
	global_store_dword v[6:7], v8, off
	s_and_saveexec_b64 s[12:13], s[38:39]
	s_cbranch_execz .LBB0_1025
	global_load_dword v4, v[4:5], off offset:768
	v_cmp_lt_i32_e32 vcc, s23, v10
	s_waitcnt vmcnt(0)
	v_lshlrev_b32_e32 v6, 16, v4
	v_and_b32_e32 v7, 0xffff0000, v4
	s_and_saveexec_b64 s[14:15], vcc
	s_xor_b64 s[14:15], exec, s[14:15]
	v_add_u32_e32 v4, 0xffffc000, v10
	v_lshrrev_b32_e32 v5, 8, v4
	v_and_b32_e32 v4, 0xff, v10
	s_andn2_saveexec_b64 s[14:15], s[14:15]
	s_cbranch_execz .LBB0_1024
	v_and_b32_e32 v4, 0x1fff, v10
	v_lshl_or_b32 v5, v4, 6, v12
	global_load_dword v8, v5, s[8:9]
	global_load_dword v28, v5, s[6:7]
	v_ashrrev_i32_e32 v5, 13, v10
	v_add_u32_e32 v4, 0x100, v4
	s_waitcnt vmcnt(1)
	v_pk_mul_f32 v[8:9], v[8:9], v[6:7] op_sel:[0,1] op_sel_hi:[0,0]
	s_waitcnt vmcnt(0)
	v_pk_mul_f32 v[36:37], v[28:29], v[6:7] op_sel_hi:[0,1]
	v_pk_fma_f32 v[6:7], v[28:29], v[6:7], v[8:9] op_sel_hi:[0,1,1]
	v_sub_f32_e32 v6, v36, v8
	s_branch .LBB0_1024
